# GEMM1: first two vmcnt waits of a tile relaxed to vmcnt(24) so epilogue stores drain under the next tile's first phases
# baseline (speedup 1.0000x reference)
; #define PG8_STAGE(bufoff, gbase, voff) do { _Pragma("unroll") for (int _i = 0; _i < 2; ++_i) \
;         __builtin_amdgcn_global_load_lds((const unsigned*)((const char*)(gbase) + (voff)[_i]), (PG8_LAS unsigned*)(lds + (bufoff) + ldsw + _i * 8192), 16, 0, 0); } while (0)
; #define PG8_WAIT_V(n) asm volatile("s_waitcnt vmcnt(" #n ")" ::: "memory")
; #define PG8_BAR __builtin_amdgcn_s_barrier()
; template <class Epi, class Sched, bool ALIGN_EPI = false, bool SP2 = false>
; __device__ __forceinline__ void gemm_phase(PG8_LAS unsigned char* lds, const Gemm g, const Sched& S, const Epi& E) {
;     ...
;     const int tid = tid_l, wid = __builtin_amdgcn_readfirstlane(tid >> 6), lane = tid & 63, wr = wid >> 2, wc = wid & 3, fr = lane & 15, fq = lane >> 4;
;     const int K = g.K, nt = K / BK;
;     unsigned voffA[2], voffB[2];
; #pragma unroll
;     for (int i = 0; i < 2; ++i) { int R, C; stage_rc(tid * 16 + i * 8192, R, C); const int Rb = Epi::PERM ? ((R & ~31) + perm32(R & 31)) : R;
;         voffA[i] = (unsigned)(R * K + C) * 2u; voffB[i] = (unsigned)(Rb * K + C) * 2u; }
;     const size_t kstep = (size_t)(BK * 2);
;     const size_t hstep = (size_t)HALF * K * 2;
;     const size_t tstep = 2 * hstep;
;     const unsigned ldsw = (unsigned)wid * 1024u;
;     const int aoff = lds_byte(wr * 64 + fr, fq * 8), boff = lds_byte(wc * 32 + fr, fq * 8);
;     ...
;         PG8_WAIT_V(2); PG8_BAR;
;         PG8_STAGE(PG8_SB(1, 0), cB + kstep, voffB); PG8_STAGE(PG8_SA(1, 0), cA + kstep, voffA); PG8_STAGE(PG8_SB(1, 1), cB + hstep + kstep, voffB);
;         PG8_WAIT_V(6); PG8_BAR;
.LBB0_147:
	s_and_b32 s15, s0, 3
	s_add_i32 m0, s93, 0x18000
	v_lshl_add_u64 v[6:7], v[6:7], 0, s[10:11]
	s_lshl_b32 s82, s1, 6
	s_lshl_b32 s22, s1, 13
	s_lshl_b32 s23, s15, 5
	s_lshl_b32 s15, s15, 12
	s_waitcnt vmcnt(2)
	s_barrier
	global_load_lds_dwordx4 v[6:7], off
	v_lshl_add_u64 v[4:5], v[4:5], 0, s[10:11]
	s_add_i32 m0, s93, 0x1a000
	s_add_i32 s36, s93, 0x8000
	s_add_i32 s37, s93, 0xa000
	global_load_lds_dwordx4 v[4:5], off
	v_lshl_add_u64 v[2:3], v[2:3], 0, s[10:11]
	s_mov_b32 m0, s36
	s_add_u32 s20, s28, 0x40080
	global_load_lds_dwordx4 v[2:3], off
	v_lshl_add_u64 v[2:3], v[8:9], 0, s[10:11]
	s_mov_b32 m0, s37
	s_addc_u32 s21, s29, 0
	global_load_lds_dwordx4 v[2:3], off
	s_add_i32 m0, s93, 0x1c000
	v_lshl_add_u64 v[2:3], s[20:21], 0, v[132:133]
	global_load_lds_dwordx4 v[2:3], off
	v_lshl_add_u64 v[2:3], s[20:21], 0, v[136:137]
	s_add_i32 m0, s93, 0x1e000
	v_and_b32_e32 v159, 15, v0
	global_load_lds_dwordx4 v[2:3], off
	v_lshrrev_b32_e32 v0, 1, v0
	v_and_b32_e32 v0, 24, v0
	s_cmpk_lt_u32 s14, 0x100
	s_cselect_b64 s[20:21], -1, 0
	v_or_b32_e32 v161, s23, v0
	v_bitop3_b32 v178, s23, 56, v0 bitop3:0xc8
	s_bitset1_b32 s23, 7
	v_lshlrev_b32_e32 v2, 1, v0
	v_lshlrev_b32_e32 v3, 2, v159
	v_or_b32_e32 v179, s23, v0
	v_bitop3_b32 v180, s23, 56, v0 bitop3:0xc8
	v_lshlrev_b32_e32 v0, 14, v10
	v_lshl_or_b32 v2, v159, 6, v2
	v_and_b32_e32 v4, 32, v3
	v_and_b32_e32 v0, 0xffff8000, v0
	v_bitop3_b32 v5, v2, s22, v4 bitop3:0xde
	v_bitop3_b32 v160, v2, s15, v4 bitop3:0xde
	v_lshl_add_u32 v0, v11, 11, v0
	v_and_b32_e32 v2, 1, v10
	v_lshl_or_b32 v0, v2, 6, v0
	v_lshl_add_u32 v138, v12, 1, v0
	v_lshlrev_b32_e32 v0, 14, v13
	s_bfe_u32 s14, s0, 0x10001
	s_lshl_b32 s0, s1, 8
	v_and_b32_e32 v0, 0xffff8000, v0
	s_waitcnt vmcnt(6)
	s_add_i32 s0, s0, 0
	v_lshl_add_u32 v0, v14, 11, v0
	v_and_b32_e32 v2, 1, v13
	s_add_i32 s0, s0, 0x20000
	v_lshl_or_b32 v0, v2, 6, v0
	s_lshr_b32 s15, s23, 6
	v_add_u32_e32 v181, s0, v3
	v_mov_b32_e32 v139, v1
	v_lshl_add_u32 v140, v15, 1, v0
	v_mov_b32_e32 v141, v1
	s_mov_b32 s0, 0
	s_mov_b32 s70, 0
	v_add_u32_e32 v182, 0, v5
	s_barrier
	s_branch .LBB0_150

; #define PG8_STAGE(bufoff, gbase, voff) do { _Pragma("unroll") for (int _i = 0; _i < 2; ++_i) \
;         __builtin_amdgcn_global_load_lds((const unsigned*)((const char*)(gbase) + (voff)[_i]), (PG8_LAS unsigned*)(lds + (bufoff) + ldsw + _i * 8192), 16, 0, 0); } while (0)
; #define PG8_LDA(dst, b, h) do { _Pragma("unroll") for (int m = 0; m < 4; ++m) _Pragma("unroll") for (int k = 0; k < 2; ++k) dst[m][k] = *(const PG8_LAS bf16x8*)(lds + PG8_SA(b, h) + aoff + m * 2048 + k * 1024); } while (0)
; #define PG8_LDB(dst, b, h) do { _Pragma("unroll") for (int n = 0; n < 2; ++n) _Pragma("unroll") for (int k = 0; k < 2; ++k) dst[n][k] = *(const PG8_LAS bf16x8*)(lds + PG8_SB(b, h) + boff + n * 2048 + k * 1024); } while (0)
; #define PG8_WAIT_V(n) asm volatile("s_waitcnt vmcnt(" #n ")" ::: "memory")
; #define PG8_WAIT_L(n) asm volatile("s_waitcnt lgkmcnt(" #n ")" ::: "memory")
; #define PG8_BAR __builtin_amdgcn_s_barrier()
; #define PG8_SCHED __builtin_amdgcn_sched_barrier(0)
; template <class Epi, class Sched, bool ALIGN_EPI = false, bool SP2 = false>
; __device__ __forceinline__ void gemm_phase(PG8_LAS unsigned char* lds, const Gemm g, const Sched& S, const Epi& E) {
;     ...
;         for (int t = 0; t < nt; t += 2) {
;             const bool last = (t == nt - 2);
;             const char* a1 = cA + (size_t)(t + 1) * kstep;
;             const char* a2 = last ? nA : cA + (size_t)(t + 2) * kstep; const char* b2 = last ? nB : cB + (size_t)(t + 2) * kstep;
;             const char* a3 = a2 + kstep; const char* b3 = b2 + kstep;
;             if (last && has_next) S.a_ready(nxt);
;             if constexpr (SP2) {
;             PG8_LDB(B0, 0, 0); PG8_LDB(B1, 0, 1); PG8_SCHED; PG8_LDA(At, 0, 0); PG8_STAGE(PG8_SA(1, 1), a1 + hstep, voffA);
;             PG8_WAIT_V(8); PG8_WAIT_L(0); PG8_BAR; PG8_MMA(0, 0, At, B0); PG8_MMA(0, 1, At, B1); PG8_BAR; PG8_SCHED;
;             PG8_LDA(At, 0, 1); PG8_STAGE(PG8_SB(0, 0), b2, voffB); PG8_STAGE(PG8_SB(0, 1), b2 + hstep, voffB); PG8_STAGE(PG8_SA(0, 0), a2, voffA);
.LBB0_153:
	s_add_u32 s28, s26, 0xfffc0080
	s_addc_u32 s29, s27, -1
	s_add_i32 s54, 0, 0x10000
	s_cmp_eq_u32 s45, 12
	s_cselect_b32 s31, s1, s29
	s_cselect_b32 s30, s25, s28
	v_add_u32_e32 v0, s54, v160
	s_cselect_b32 s29, s23, s43
	s_cselect_b32 s28, s41, s42
	s_add_i32 s56, 0, 0x14000
	ds_read_b128 v[142:145], v0
	ds_read_b128 v[146:149], v0 offset:1024
	ds_read_b128 v[150:153], v0 offset:2048
	ds_read_b128 v[154:157], v0 offset:3072
	v_add_u32_e32 v0, s56, v160
	ds_read_b128 v[184:187], v0
	ds_read_b128 v[188:191], v0 offset:1024
	ds_read_b128 v[192:195], v0 offset:2048
	ds_read_b128 v[196:199], v0 offset:3072
	v_lshl_add_u64 v[244:245], s[26:27], 0, v[138:139]
	s_add_i32 m0, s93, 0xc000
	ds_read_b128 v[200:203], v182
	ds_read_b128 v[204:207], v182 offset:1024
	ds_read_b128 v[208:211], v182 offset:2048
	ds_read_b128 v[212:215], v182 offset:3072
	ds_read_b128 v[216:219], v182 offset:4096
	ds_read_b128 v[220:223], v182 offset:5120
	ds_read_b128 v[236:239], v182 offset:6144
	ds_read_b128 v[240:243], v182 offset:7168
	global_load_lds_dwordx4 v[244:245], off
	v_lshl_add_u64 v[244:245], s[26:27], 0, v[140:141]
	s_add_i32 m0, s93, 0xe000
	s_nop 0
	global_load_lds_dwordx4 v[244:245], off
	s_cmp_eq_u32 s70, 0
	s_cbranch_scc1 .Lg1w1_n
	s_waitcnt vmcnt(24)
	s_branch .Lg1w1_d
.Lg1w1_n:
	s_waitcnt vmcnt(8)
.Lg1w1_d:
	s_waitcnt lgkmcnt(0)
	s_barrier
	s_setprio 1
	s_waitcnt lgkmcnt(0)
	v_mfma_f32_16x16x32_f16 v[126:129], v[142:145], v[200:203], v[126:129]
	v_mfma_f32_16x16x32_f16 v[122:125], v[150:153], v[200:203], v[122:125]
	v_mfma_f32_16x16x32_f16 v[110:113], v[142:145], v[208:211], v[110:113]
	v_mfma_f32_16x16x32_f16 v[106:109], v[150:153], v[208:211], v[106:109]
	v_mfma_f32_16x16x32_f16 v[94:97], v[142:145], v[216:219], v[94:97]
	v_mfma_f32_16x16x32_f16 v[90:93], v[150:153], v[216:219], v[90:93]
	v_mfma_f32_16x16x32_f16 v[78:81], v[142:145], v[236:239], v[78:81]
	v_mfma_f32_16x16x32_f16 v[74:77], v[150:153], v[236:239], v[74:77]
	v_mfma_f32_16x16x32_f16 v[126:129], v[146:149], v[204:207], v[126:129]
	v_mfma_f32_16x16x32_f16 v[122:125], v[154:157], v[204:207], v[122:125]
	v_mfma_f32_16x16x32_f16 v[110:113], v[146:149], v[212:215], v[110:113]
	v_mfma_f32_16x16x32_f16 v[106:109], v[154:157], v[212:215], v[106:109]
	v_mfma_f32_16x16x32_f16 v[94:97], v[146:149], v[220:223], v[94:97]
	v_mfma_f32_16x16x32_f16 v[90:93], v[154:157], v[220:223], v[90:93]
	v_mfma_f32_16x16x32_f16 v[78:81], v[146:149], v[240:243], v[78:81]
	v_mfma_f32_16x16x32_f16 v[74:77], v[154:157], v[240:243], v[74:77]
	s_setprio 0
	s_setprio 1
	v_mfma_f32_16x16x32_f16 v[118:121], v[184:187], v[200:203], v[118:121]
	v_mfma_f32_16x16x32_f16 v[114:117], v[192:195], v[200:203], v[114:117]
	v_mfma_f32_16x16x32_f16 v[102:105], v[184:187], v[208:211], v[102:105]
	v_mfma_f32_16x16x32_f16 v[98:101], v[192:195], v[208:211], v[98:101]
	v_mfma_f32_16x16x32_f16 v[86:89], v[184:187], v[216:219], v[86:89]
	v_mfma_f32_16x16x32_f16 v[82:85], v[192:195], v[216:219], v[82:85]
	v_mfma_f32_16x16x32_f16 v[70:73], v[184:187], v[236:239], v[70:73]
	v_mfma_f32_16x16x32_f16 v[66:69], v[192:195], v[236:239], v[66:69]
	v_mfma_f32_16x16x32_f16 v[118:121], v[188:191], v[204:207], v[118:121]
	v_mfma_f32_16x16x32_f16 v[114:117], v[196:199], v[204:207], v[114:117]
	v_mfma_f32_16x16x32_f16 v[102:105], v[188:191], v[212:215], v[102:105]
	v_mfma_f32_16x16x32_f16 v[98:101], v[196:199], v[212:215], v[98:101]
	v_mfma_f32_16x16x32_f16 v[86:89], v[188:191], v[220:223], v[86:89]
	v_mfma_f32_16x16x32_f16 v[82:85], v[196:199], v[220:223], v[82:85]
	v_mfma_f32_16x16x32_f16 v[70:73], v[188:191], v[240:243], v[70:73]
	v_mfma_f32_16x16x32_f16 v[66:69], v[196:199], v[240:243], v[66:69]
	s_setprio 0
	s_barrier
	s_add_i32 s54, s54, s16
	v_lshl_add_u64 v[244:245], s[28:29], 0, v[132:133]
	s_mov_b32 m0, s54
	ds_read_b128 v[200:203], v182 offset:16384
	ds_read_b128 v[204:207], v182 offset:17408
	ds_read_b128 v[208:211], v182 offset:18432
	ds_read_b128 v[212:215], v182 offset:19456
	ds_read_b128 v[216:219], v182 offset:20480
	ds_read_b128 v[220:223], v182 offset:21504
	ds_read_b128 v[236:239], v182 offset:22528
	ds_read_b128 v[240:243], v182 offset:23552
	global_load_lds_dwordx4 v[244:245], off
	s_add_i32 m0, s54, 0x2000
	s_add_u32 s54, s28, 0x40000
	v_lshl_add_u64 v[246:247], s[28:29], 0, v[136:137]
	s_addc_u32 s55, s29, 0
	s_add_i32 s56, s56, s16
	global_load_lds_dwordx4 v[246:247], off
	v_lshl_add_u64 v[248:249], s[54:55], 0, v[132:133]
	s_mov_b32 m0, s56
	v_lshl_add_u64 v[250:251], s[30:31], 0, v[134:135]
	global_load_lds_dwordx4 v[248:249], off
	v_lshl_add_u64 v[248:249], s[54:55], 0, v[136:137]
	s_add_i32 m0, s56, 0x2000
	s_nop 0
	global_load_lds_dwordx4 v[248:249], off
	v_lshl_add_u64 v[248:249], s[30:31], 0, v[130:131]
	s_mov_b32 m0, s93
	s_nop 0
	global_load_lds_dwordx4 v[248:249], off
	s_mov_b32 m0, s13
	s_nop 0
	global_load_lds_dwordx4 v[250:251], off
	s_cmp_eq_u32 s70, 0
	s_cbranch_scc1 .Lg1w2_n
	s_waitcnt vmcnt(24)
	s_branch .Lg1w2_d

; #define PG8_STAGE(bufoff, gbase, voff) do { _Pragma("unroll") for (int _i = 0; _i < 2; ++_i) \
;         __builtin_amdgcn_global_load_lds((const unsigned*)((const char*)(gbase) + (voff)[_i]), (PG8_LAS unsigned*)(lds + (bufoff) + ldsw + _i * 8192), 16, 0, 0); } while (0)
; #define PG8_LDA(dst, b, h) do { _Pragma("unroll") for (int m = 0; m < 4; ++m) _Pragma("unroll") for (int k = 0; k < 2; ++k) dst[m][k] = *(const PG8_LAS bf16x8*)(lds + PG8_SA(b, h) + aoff + m * 2048 + k * 1024); } while (0)
; #define PG8_LDB(dst, b, h) do { _Pragma("unroll") for (int n = 0; n < 2; ++n) _Pragma("unroll") for (int k = 0; k < 2; ++k) dst[n][k] = *(const PG8_LAS bf16x8*)(lds + PG8_SB(b, h) + boff + n * 2048 + k * 1024); } while (0)
; #define PG8_WAIT_V(n) asm volatile("s_waitcnt vmcnt(" #n ")" ::: "memory")
; #define PG8_WAIT_L(n) asm volatile("s_waitcnt lgkmcnt(" #n ")" ::: "memory")
; #define PG8_BAR __builtin_amdgcn_s_barrier()
; #define PG8_SCHED __builtin_amdgcn_sched_barrier(0)
; template <class Epi, class Sched, bool ALIGN_EPI = false, bool SP2 = false>
; __device__ __forceinline__ void gemm_phase(PG8_LAS unsigned char* lds, const Gemm g, const Sched& S, const Epi& E) {
;     ...
;             PG8_LDA(At, 0, 1); PG8_STAGE(PG8_SB(0, 0), b2, voffB); PG8_STAGE(PG8_SB(0, 1), b2 + hstep, voffB); PG8_STAGE(PG8_SA(0, 0), a2, voffA);
;             PG8_WAIT_V(8); PG8_WAIT_L(0); PG8_BAR; PG8_MMA(1, 0, At, B0); PG8_MMA(1, 1, At, B1); PG8_BAR; PG8_SCHED;
;             PG8_LDB(B0, 1, 0); PG8_LDB(B1, 1, 1); PG8_SCHED; PG8_LDA(At, 1, 0); PG8_STAGE(PG8_SA(0, 1), a2 + hstep, voffA);
;             PG8_WAIT_V(8); PG8_WAIT_L(0); PG8_BAR; PG8_MMA(0, 0, At, B0); PG8_MMA(0, 1, At, B1); PG8_BAR; PG8_SCHED;
.Lg1w2_d:
	s_mov_b32 s70, 0
	s_waitcnt lgkmcnt(0)
	s_barrier
	s_setprio 1
	s_waitcnt lgkmcnt(0)
	v_mfma_f32_16x16x32_f16 v[62:65], v[142:145], v[200:203], v[62:65]
	v_mfma_f32_16x16x32_f16 v[58:61], v[150:153], v[200:203], v[58:61]
	v_mfma_f32_16x16x32_f16 v[46:49], v[142:145], v[208:211], v[46:49]
	v_mfma_f32_16x16x32_f16 v[42:45], v[150:153], v[208:211], v[42:45]
	v_mfma_f32_16x16x32_f16 v[30:33], v[142:145], v[216:219], v[30:33]
	v_mfma_f32_16x16x32_f16 v[26:29], v[150:153], v[216:219], v[26:29]
	v_mfma_f32_16x16x32_f16 v[14:17], v[142:145], v[236:239], v[14:17]
	v_mfma_f32_16x16x32_f16 v[10:13], v[150:153], v[236:239], v[10:13]
	v_mfma_f32_16x16x32_f16 v[62:65], v[146:149], v[204:207], v[62:65]
	v_mfma_f32_16x16x32_f16 v[58:61], v[154:157], v[204:207], v[58:61]
	v_mfma_f32_16x16x32_f16 v[46:49], v[146:149], v[212:215], v[46:49]
	v_mfma_f32_16x16x32_f16 v[42:45], v[154:157], v[212:215], v[42:45]
	v_mfma_f32_16x16x32_f16 v[30:33], v[146:149], v[220:223], v[30:33]
	v_mfma_f32_16x16x32_f16 v[26:29], v[154:157], v[220:223], v[26:29]
	v_mfma_f32_16x16x32_f16 v[14:17], v[146:149], v[240:243], v[14:17]
	v_mfma_f32_16x16x32_f16 v[10:13], v[154:157], v[240:243], v[10:13]
	s_setprio 0
	s_setprio 1
	v_mfma_f32_16x16x32_f16 v[54:57], v[184:187], v[200:203], v[54:57]
	v_mfma_f32_16x16x32_f16 v[50:53], v[192:195], v[200:203], v[50:53]
	v_mfma_f32_16x16x32_f16 v[38:41], v[184:187], v[208:211], v[38:41]
	v_mfma_f32_16x16x32_f16 v[34:37], v[192:195], v[208:211], v[34:37]
	v_mfma_f32_16x16x32_f16 v[22:25], v[184:187], v[216:219], v[22:25]
	v_mfma_f32_16x16x32_f16 v[18:21], v[192:195], v[216:219], v[18:21]
	v_mfma_f32_16x16x32_f16 v[6:9], v[184:187], v[236:239], v[6:9]
	v_mfma_f32_16x16x32_f16 v[2:5], v[192:195], v[236:239], v[2:5]
	v_mfma_f32_16x16x32_f16 v[54:57], v[188:191], v[204:207], v[54:57]
	v_mfma_f32_16x16x32_f16 v[50:53], v[196:199], v[204:207], v[50:53]
	v_mfma_f32_16x16x32_f16 v[38:41], v[188:191], v[212:215], v[38:41]
	v_mfma_f32_16x16x32_f16 v[34:37], v[196:199], v[212:215], v[34:37]
	v_mfma_f32_16x16x32_f16 v[22:25], v[188:191], v[220:223], v[22:25]
	v_mfma_f32_16x16x32_f16 v[18:21], v[196:199], v[220:223], v[18:21]
	v_mfma_f32_16x16x32_f16 v[6:9], v[188:191], v[240:243], v[6:9]
	v_mfma_f32_16x16x32_f16 v[2:5], v[196:199], v[240:243], v[2:5]
	s_setprio 0
	s_barrier
	s_add_i32 s54, 0, 0x18000
	v_add_u32_e32 v0, s54, v160
	s_add_i32 s55, 0, 0x1c000
	ds_read_b128 v[142:145], v0
	ds_read_b128 v[146:149], v0 offset:1024
	ds_read_b128 v[150:153], v0 offset:2048
	ds_read_b128 v[154:157], v0 offset:3072
	v_add_u32_e32 v0, s55, v160
	ds_read_b128 v[184:187], v0
	ds_read_b128 v[188:191], v0 offset:1024
	ds_read_b128 v[192:195], v0 offset:2048
	ds_read_b128 v[196:199], v0 offset:3072
	s_add_u32 s30, s30, 0x40000
	s_addc_u32 s31, s31, 0
	s_mov_b32 m0, s68
	v_lshl_add_u64 v[172:173], s[30:31], 0, v[130:131]
	ds_read_b128 v[200:203], v182 offset:32768
	ds_read_b128 v[204:207], v182 offset:33792
	ds_read_b128 v[208:211], v182 offset:34816
	ds_read_b128 v[212:215], v182 offset:35840
	ds_read_b128 v[216:219], v182 offset:36864
	ds_read_b128 v[220:223], v182 offset:37888
	ds_read_b128 v[236:239], v182 offset:38912
	ds_read_b128 v[240:243], v182 offset:39936
	global_load_lds_dwordx4 v[172:173], off
	v_lshl_add_u64 v[172:173], s[30:31], 0, v[134:135]
	s_mov_b32 m0, s72
	s_nop 0
	global_load_lds_dwordx4 v[172:173], off
	s_waitcnt vmcnt(8)
	s_waitcnt lgkmcnt(0)
	s_barrier
	s_setprio 1
	s_waitcnt lgkmcnt(0)
	v_mfma_f32_16x16x32_f16 v[126:129], v[142:145], v[200:203], v[126:129]
	v_mfma_f32_16x16x32_f16 v[122:125], v[150:153], v[200:203], v[122:125]
	v_mfma_f32_16x16x32_f16 v[110:113], v[142:145], v[208:211], v[110:113]
	v_mfma_f32_16x16x32_f16 v[106:109], v[150:153], v[208:211], v[106:109]
	v_mfma_f32_16x16x32_f16 v[94:97], v[142:145], v[216:219], v[94:97]
	v_mfma_f32_16x16x32_f16 v[90:93], v[150:153], v[216:219], v[90:93]
	v_mfma_f32_16x16x32_f16 v[78:81], v[142:145], v[236:239], v[78:81]
	v_mfma_f32_16x16x32_f16 v[74:77], v[150:153], v[236:239], v[74:77]
	v_mfma_f32_16x16x32_f16 v[126:129], v[146:149], v[204:207], v[126:129]
	v_mfma_f32_16x16x32_f16 v[122:125], v[154:157], v[204:207], v[122:125]
	v_mfma_f32_16x16x32_f16 v[110:113], v[146:149], v[212:215], v[110:113]
	v_mfma_f32_16x16x32_f16 v[106:109], v[154:157], v[212:215], v[106:109]
	v_mfma_f32_16x16x32_f16 v[94:97], v[146:149], v[220:223], v[94:97]
	v_mfma_f32_16x16x32_f16 v[90:93], v[154:157], v[220:223], v[90:93]
	v_mfma_f32_16x16x32_f16 v[78:81], v[146:149], v[240:243], v[78:81]
	v_mfma_f32_16x16x32_f16 v[74:77], v[154:157], v[240:243], v[74:77]
	s_setprio 0
	s_setprio 1
	v_mfma_f32_16x16x32_f16 v[118:121], v[184:187], v[200:203], v[118:121]
	v_mfma_f32_16x16x32_f16 v[114:117], v[192:195], v[200:203], v[114:117]
	v_mfma_f32_16x16x32_f16 v[102:105], v[184:187], v[208:211], v[102:105]
	v_mfma_f32_16x16x32_f16 v[98:101], v[192:195], v[208:211], v[98:101]
	v_mfma_f32_16x16x32_f16 v[86:89], v[184:187], v[216:219], v[86:89]
	v_mfma_f32_16x16x32_f16 v[82:85], v[192:195], v[216:219], v[82:85]
	v_mfma_f32_16x16x32_f16 v[70:73], v[184:187], v[236:239], v[70:73]
	v_mfma_f32_16x16x32_f16 v[66:69], v[192:195], v[236:239], v[66:69]
	v_mfma_f32_16x16x32_f16 v[118:121], v[188:191], v[204:207], v[118:121]
	v_mfma_f32_16x16x32_f16 v[114:117], v[196:199], v[204:207], v[114:117]
	v_mfma_f32_16x16x32_f16 v[102:105], v[188:191], v[212:215], v[102:105]
	v_mfma_f32_16x16x32_f16 v[98:101], v[196:199], v[212:215], v[98:101]
	v_mfma_f32_16x16x32_f16 v[86:89], v[188:191], v[220:223], v[86:89]
	v_mfma_f32_16x16x32_f16 v[82:85], v[196:199], v[220:223], v[82:85]
	v_mfma_f32_16x16x32_f16 v[70:73], v[188:191], v[240:243], v[70:73]
	v_mfma_f32_16x16x32_f16 v[66:69], v[196:199], v[240:243], v[66:69]
	s_setprio 0
	s_barrier
; #define PG8_STAGE(bufoff, gbase, voff) do { _Pragma("unroll") for (int _i = 0; _i < 2; ++_i) \
;         __builtin_amdgcn_global_load_lds((const unsigned*)((const char*)(gbase) + (voff)[_i]), (PG8_LAS unsigned*)(lds + (bufoff) + ldsw + _i * 8192), 16, 0, 0); } while (0)
; #define PG8_LDA(dst, b, h) do { _Pragma("unroll") for (int m = 0; m < 4; ++m) _Pragma("unroll") for (int k = 0; k < 2; ++k) dst[m][k] = *(const PG8_LAS bf16x8*)(lds + PG8_SA(b, h) + aoff + m * 2048 + k * 1024); } while (0)
; #define PG8_LDB(dst, b, h) do { _Pragma("unroll") for (int n = 0; n < 2; ++n) _Pragma("unroll") for (int k = 0; k < 2; ++k) dst[n][k] = *(const PG8_LAS bf16x8*)(lds + PG8_SB(b, h) + boff + n * 2048 + k * 1024); } while (0)
; #define PG8_WAIT_V(n) asm volatile("s_waitcnt vmcnt(" #n ")" ::: "memory")
; #define PG8_WAIT_L(n) asm volatile("s_waitcnt lgkmcnt(" #n ")" ::: "memory")
; #define PG8_BAR __builtin_amdgcn_s_barrier()
; #define PG8_SCHED __builtin_amdgcn_sched_barrier(0)
; template <class Epi, class Sched, bool ALIGN_EPI = false, bool SP2 = false>
; __device__ __forceinline__ void gemm_phase(PG8_LAS unsigned char* lds, const Gemm g, const Sched& S, const Epi& E) {
;     ...
;             PG8_LDB(B0, 1, 0); PG8_LDB(B1, 1, 1); PG8_SCHED; PG8_LDA(At, 1, 0); PG8_STAGE(PG8_SA(0, 1), a2 + hstep, voffA);
;             PG8_WAIT_V(8); PG8_WAIT_L(0); PG8_BAR; PG8_MMA(0, 0, At, B0); PG8_MMA(0, 1, At, B1); PG8_BAR; PG8_SCHED;
;             PG8_LDA(At, 1, 1); PG8_STAGE(PG8_SB(1, 0), b3, voffB); PG8_STAGE(PG8_SB(1, 1), b3 + hstep, voffB); PG8_STAGE(PG8_SA(1, 0), a3, voffA);
;             PG8_WAIT_V(8); PG8_WAIT_L(0); PG8_BAR; PG8_MMA(1, 0, At, B0); PG8_MMA(1, 1, At, B1); PG8_BAR; PG8_SCHED;
	s_add_i32 s30, s54, s16
	v_lshl_add_u64 v[172:173], v[244:245], 0, s[10:11]
	s_mov_b32 m0, s30
	ds_read_b128 v[200:203], v182 offset:49152
	ds_read_b128 v[204:207], v182 offset:50176
	ds_read_b128 v[208:211], v182 offset:51200
	ds_read_b128 v[212:215], v182 offset:52224
	ds_read_b128 v[216:219], v182 offset:53248
	ds_read_b128 v[220:223], v182 offset:54272
	ds_read_b128 v[236:239], v182 offset:55296
	ds_read_b128 v[240:243], v182 offset:56320
	global_load_lds_dwordx4 v[172:173], off
	s_add_i32 m0, s30, 0x2000
	s_add_u32 s28, s28, 0x40080
	v_lshl_add_u64 v[172:173], v[246:247], 0, s[10:11]
	s_addc_u32 s29, s29, 0
	s_add_i32 s30, s55, s16
	global_load_lds_dwordx4 v[172:173], off
	v_lshl_add_u64 v[172:173], s[28:29], 0, v[132:133]
	s_mov_b32 m0, s30
	s_nop 0
	global_load_lds_dwordx4 v[172:173], off
	v_lshl_add_u64 v[172:173], s[28:29], 0, v[136:137]
	s_add_i32 m0, s30, 0x2000
	s_nop 0
	global_load_lds_dwordx4 v[172:173], off
	v_lshl_add_u64 v[172:173], v[248:249], 0, s[10:11]
	s_mov_b32 m0, s36
	s_nop 0
	global_load_lds_dwordx4 v[172:173], off
	v_lshl_add_u64 v[172:173], v[250:251], 0, s[10:11]
	s_mov_b32 m0, s37
	s_nop 0
	global_load_lds_dwordx4 v[172:173], off
	s_waitcnt vmcnt(8)
	s_waitcnt lgkmcnt(0)
	s_barrier
	s_setprio 1
	s_waitcnt lgkmcnt(0)
	v_mfma_f32_16x16x32_f16 v[62:65], v[142:145], v[200:203], v[62:65]
	v_mfma_f32_16x16x32_f16 v[58:61], v[150:153], v[200:203], v[58:61]
	v_mfma_f32_16x16x32_f16 v[46:49], v[142:145], v[208:211], v[46:49]
	v_mfma_f32_16x16x32_f16 v[42:45], v[150:153], v[208:211], v[42:45]
	v_mfma_f32_16x16x32_f16 v[30:33], v[142:145], v[216:219], v[30:33]
	v_mfma_f32_16x16x32_f16 v[26:29], v[150:153], v[216:219], v[26:29]
	v_mfma_f32_16x16x32_f16 v[14:17], v[142:145], v[236:239], v[14:17]
	v_mfma_f32_16x16x32_f16 v[10:13], v[150:153], v[236:239], v[10:13]
	v_mfma_f32_16x16x32_f16 v[62:65], v[146:149], v[204:207], v[62:65]
	v_mfma_f32_16x16x32_f16 v[58:61], v[154:157], v[204:207], v[58:61]
	v_mfma_f32_16x16x32_f16 v[46:49], v[146:149], v[212:215], v[46:49]
	v_mfma_f32_16x16x32_f16 v[42:45], v[154:157], v[212:215], v[42:45]
	v_mfma_f32_16x16x32_f16 v[30:33], v[146:149], v[220:223], v[30:33]
	v_mfma_f32_16x16x32_f16 v[26:29], v[154:157], v[220:223], v[26:29]
	v_mfma_f32_16x16x32_f16 v[14:17], v[146:149], v[240:243], v[14:17]
	v_mfma_f32_16x16x32_f16 v[10:13], v[154:157], v[240:243], v[10:13]
	s_setprio 0
	s_setprio 1
	v_mfma_f32_16x16x32_f16 v[54:57], v[184:187], v[200:203], v[54:57]
	v_mfma_f32_16x16x32_f16 v[50:53], v[192:195], v[200:203], v[50:53]
	v_mfma_f32_16x16x32_f16 v[38:41], v[184:187], v[208:211], v[38:41]
	v_mfma_f32_16x16x32_f16 v[34:37], v[192:195], v[208:211], v[34:37]
	v_mfma_f32_16x16x32_f16 v[22:25], v[184:187], v[216:219], v[22:25]
	v_mfma_f32_16x16x32_f16 v[18:21], v[192:195], v[216:219], v[18:21]
	v_mfma_f32_16x16x32_f16 v[6:9], v[184:187], v[236:239], v[6:9]
	v_mfma_f32_16x16x32_f16 v[2:5], v[192:195], v[236:239], v[2:5]
	v_mfma_f32_16x16x32_f16 v[54:57], v[188:191], v[204:207], v[54:57]
	v_mfma_f32_16x16x32_f16 v[50:53], v[196:199], v[204:207], v[50:53]
	v_mfma_f32_16x16x32_f16 v[38:41], v[188:191], v[212:215], v[38:41]
	v_mfma_f32_16x16x32_f16 v[34:37], v[196:199], v[212:215], v[34:37]
	v_mfma_f32_16x16x32_f16 v[22:25], v[188:191], v[220:223], v[22:25]
	v_mfma_f32_16x16x32_f16 v[18:21], v[196:199], v[220:223], v[18:21]
	v_mfma_f32_16x16x32_f16 v[6:9], v[188:191], v[240:243], v[6:9]
	v_mfma_f32_16x16x32_f16 v[2:5], v[196:199], v[240:243], v[2:5]
	s_setprio 0
	s_barrier
	s_add_i32 s45, s45, 2
	s_add_u32 s26, s26, 0x100
	s_addc_u32 s27, s27, 0
	s_add_u32 s42, s42, 0x100
	s_addc_u32 s43, s43, 0
	s_cmp_gt_u32 s45, 13
	s_cbranch_scc0 .LBB0_153
	s_and_b64 vcc, exec, s[20:21]
	s_cbranch_vccz .LBB0_156
	s_barrier

; __device__ __forceinline__ unsigned cvtpk(float lo, float hi) { f32x2_t v = {lo, hi}; f16x2_t b = __builtin_convertvector(v, f16x2_t); return __builtin_bit_cast(unsigned, b); }
;     __device__ __forceinline__ void operator()(const f32x4 (&acc)[2][2][4][2], const Unit& u, int wr, int wc, int fr, int fq) const {
;     ...
; #pragma unroll
;         for (int ai = 0; ai < 2; ++ai)
; #pragma unroll
;             for (int m = 0; m < 4; ++m) { const int row = row0 + ai * HALF + m * 16; const int bl = row >> 12, t = row & 4095;
; #pragma unroll
;                 for (int bj = 0; bj < 2; ++bj) { const f32x4 v0 = acc[ai][bj][m][0] * rs[ai][m], v1 = acc[ai][bj][m][1] * rs[ai][m];
;                     u32x4 w; w.x = cvtpk(v0[0], v0[1]); w.y = cvtpk(v0[2], v0[3]); w.z = cvtpk(v1[0], v1[1]); w.w = cvtpk(v1[2], v1[3]);
;                     const int ct = bj * HALF + wc * 32 + 8 * fq;
;                     bf16_t* dst;
;                     if (pn < 18) { const int sect = pn / 6, hh = (pn - sect * 6) * 4 + (ct >> 6), dsh = 2 * (hh >> 3); const int idx = ((t & ((1 << dsh) - 1)) << (12 - dsh)) + (t >> dsh);
;                         dst = P + PL_A + ((size_t)((bl * 3 + sect) * 24 + hh) * 4096 + idx) * 64 + (ct & 63); }
;                     else if (pn < 22) { const int qk = (pn - 18) >> 1, head = ((pn - 18) & 1) * 2 + (ct >> 7);
;                         dst = P + PL_QR + (size_t)qk * PL_QK_SZ + ((size_t)(bl * 4 + head) * 4096 + t) * 128 + (ct & 127); }
;                     else if (pn < 30) { const int vg = (pn - 22) >> 2, head = (pn - 22) & 3;
;                         dst = P + PL_VR + (size_t)vg * PL_VG_SZ + ((size_t)(bl * 4 + head) * 4096 + t) * 256 + ct; }
;                     else dst = G + (size_t)row * 2048 + (pn - 30) * 256 + ct;
;                     *(u32x4*)dst = w; } }
.Lepi1_go:
	s_add_i32 s27, s55, s57
	s_waitcnt lgkmcnt(0)
	v_pk_mul_f32 v[126:127], v[126:127], v[150:151] op_sel_hi:[1,0]
	v_pk_mul_f32 v[128:129], v[128:129], v[150:151] op_sel_hi:[1,0]
	v_pk_mul_f32 v[122:123], v[122:123], v[150:151] op_sel_hi:[1,0]
	v_pk_mul_f32 v[124:125], v[124:125], v[150:151] op_sel_hi:[1,0]
	v_cvt_pk_f16_f32 v126, v126, v127
	v_cvt_pk_f16_f32 v127, v128, v129
	v_cvt_pk_f16_f32 v128, v122, v123
	v_cvt_pk_f16_f32 v129, v124, v125
	v_mov_b32_e32 v184, v183
	global_store_dwordx4 v184, v[126:129], s[100:101]
	v_pk_mul_f32 v[110:111], v[110:111], v[150:151] op_sel:[0,1] op_sel_hi:[1,1]
	v_pk_mul_f32 v[112:113], v[112:113], v[150:151] op_sel:[0,1] op_sel_hi:[1,1]
	v_pk_mul_f32 v[106:107], v[106:107], v[150:151] op_sel:[0,1] op_sel_hi:[1,1]
	v_pk_mul_f32 v[108:109], v[108:109], v[150:151] op_sel:[0,1] op_sel_hi:[1,1]
	v_cvt_pk_f16_f32 v110, v110, v111
	v_cvt_pk_f16_f32 v111, v112, v113
	v_cvt_pk_f16_f32 v112, v106, v107
	v_cvt_pk_f16_f32 v113, v108, v109
	v_add_u32_e32 v185, s45, v184
	global_store_dwordx4 v185, v[110:113], s[100:101]
	v_pk_mul_f32 v[94:95], v[94:95], v[148:149] op_sel_hi:[1,0]
	v_pk_mul_f32 v[96:97], v[96:97], v[148:149] op_sel_hi:[1,0]
	v_pk_mul_f32 v[90:91], v[90:91], v[148:149] op_sel_hi:[1,0]
	v_pk_mul_f32 v[92:93], v[92:93], v[148:149] op_sel_hi:[1,0]
	v_cvt_pk_f16_f32 v94, v94, v95
	v_cvt_pk_f16_f32 v95, v96, v97
	v_cvt_pk_f16_f32 v96, v90, v91
	v_cvt_pk_f16_f32 v97, v92, v93
	v_add_u32_e32 v186, s45, v185
	global_store_dwordx4 v186, v[94:97], s[100:101]
	v_pk_mul_f32 v[78:79], v[78:79], v[148:149] op_sel:[0,1] op_sel_hi:[1,1]
	v_pk_mul_f32 v[80:81], v[80:81], v[148:149] op_sel:[0,1] op_sel_hi:[1,1]
	v_pk_mul_f32 v[74:75], v[74:75], v[148:149] op_sel:[0,1] op_sel_hi:[1,1]
	v_pk_mul_f32 v[76:77], v[76:77], v[148:149] op_sel:[0,1] op_sel_hi:[1,1]
	v_cvt_pk_f16_f32 v78, v78, v79
	v_cvt_pk_f16_f32 v79, v80, v81
	v_cvt_pk_f16_f32 v80, v74, v75
	v_cvt_pk_f16_f32 v81, v76, v77
	v_add_u32_e32 v187, s45, v186
	global_store_dwordx4 v187, v[78:81], s[100:101]
	v_pk_mul_f32 v[118:119], v[118:119], v[150:151] op_sel_hi:[1,0]
	v_pk_mul_f32 v[120:121], v[120:121], v[150:151] op_sel_hi:[1,0]
	v_pk_mul_f32 v[114:115], v[114:115], v[150:151] op_sel_hi:[1,0]
	v_pk_mul_f32 v[116:117], v[116:117], v[150:151] op_sel_hi:[1,0]
	v_cvt_pk_f16_f32 v118, v118, v119
	v_cvt_pk_f16_f32 v119, v120, v121
	v_cvt_pk_f16_f32 v120, v114, v115
	v_cvt_pk_f16_f32 v121, v116, v117
	v_add_u32_e32 v184, s57, v183
	global_store_dwordx4 v184, v[118:121], s[100:101]
	v_pk_mul_f32 v[102:103], v[102:103], v[150:151] op_sel:[0,1] op_sel_hi:[1,1]
	v_pk_mul_f32 v[104:105], v[104:105], v[150:151] op_sel:[0,1] op_sel_hi:[1,1]
	v_pk_mul_f32 v[98:99], v[98:99], v[150:151] op_sel:[0,1] op_sel_hi:[1,1]
	v_pk_mul_f32 v[100:101], v[100:101], v[150:151] op_sel:[0,1] op_sel_hi:[1,1]
	v_cvt_pk_f16_f32 v102, v102, v103
	v_cvt_pk_f16_f32 v103, v104, v105
	v_cvt_pk_f16_f32 v104, v98, v99
	v_cvt_pk_f16_f32 v105, v100, v101
	v_add_u32_e32 v185, s45, v184
	global_store_dwordx4 v185, v[102:105], s[100:101]
	v_pk_mul_f32 v[86:87], v[86:87], v[148:149] op_sel_hi:[1,0]
	v_pk_mul_f32 v[88:89], v[88:89], v[148:149] op_sel_hi:[1,0]
	v_pk_mul_f32 v[82:83], v[82:83], v[148:149] op_sel_hi:[1,0]
	v_pk_mul_f32 v[84:85], v[84:85], v[148:149] op_sel_hi:[1,0]
	v_cvt_pk_f16_f32 v86, v86, v87
	v_cvt_pk_f16_f32 v87, v88, v89
	v_cvt_pk_f16_f32 v88, v82, v83
	v_cvt_pk_f16_f32 v89, v84, v85
	v_add_u32_e32 v186, s45, v185
	global_store_dwordx4 v186, v[86:89], s[100:101]
	v_pk_mul_f32 v[70:71], v[70:71], v[148:149] op_sel:[0,1] op_sel_hi:[1,1]
	v_pk_mul_f32 v[72:73], v[72:73], v[148:149] op_sel:[0,1] op_sel_hi:[1,1]
	v_pk_mul_f32 v[66:67], v[66:67], v[148:149] op_sel:[0,1] op_sel_hi:[1,1]
	v_pk_mul_f32 v[68:69], v[68:69], v[148:149] op_sel:[0,1] op_sel_hi:[1,1]
	v_cvt_pk_f16_f32 v70, v70, v71
	v_cvt_pk_f16_f32 v71, v72, v73
	v_cvt_pk_f16_f32 v72, v66, v67
	v_cvt_pk_f16_f32 v73, v68, v69
	v_add_u32_e32 v187, s45, v186
	global_store_dwordx4 v187, v[70:73], s[100:101]
	v_pk_mul_f32 v[62:63], v[62:63], v[146:147] op_sel_hi:[1,0]
	v_pk_mul_f32 v[64:65], v[64:65], v[146:147] op_sel_hi:[1,0]
	v_pk_mul_f32 v[58:59], v[58:59], v[146:147] op_sel_hi:[1,0]
; __device__ __forceinline__ unsigned cvtpk(float lo, float hi) { f32x2_t v = {lo, hi}; f16x2_t b = __builtin_convertvector(v, f16x2_t); return __builtin_bit_cast(unsigned, b); }
;     __device__ __forceinline__ void operator()(const f32x4 (&acc)[2][2][4][2], const Unit& u, int wr, int wc, int fr, int fq) const {
;     ...
; #pragma unroll
;         for (int ai = 0; ai < 2; ++ai)
; #pragma unroll
;             for (int m = 0; m < 4; ++m) { const int row = row0 + ai * HALF + m * 16; const int bl = row >> 12, t = row & 4095;
; #pragma unroll
;                 for (int bj = 0; bj < 2; ++bj) { const f32x4 v0 = acc[ai][bj][m][0] * rs[ai][m], v1 = acc[ai][bj][m][1] * rs[ai][m];
;                     u32x4 w; w.x = cvtpk(v0[0], v0[1]); w.y = cvtpk(v0[2], v0[3]); w.z = cvtpk(v1[0], v1[1]); w.w = cvtpk(v1[2], v1[3]);
;                     const int ct = bj * HALF + wc * 32 + 8 * fq;
;                     bf16_t* dst;
;                     if (pn < 18) { const int sect = pn / 6, hh = (pn - sect * 6) * 4 + (ct >> 6), dsh = 2 * (hh >> 3); const int idx = ((t & ((1 << dsh) - 1)) << (12 - dsh)) + (t >> dsh);
;                         dst = P + PL_A + ((size_t)((bl * 3 + sect) * 24 + hh) * 4096 + idx) * 64 + (ct & 63); }
;                     else if (pn < 22) { const int qk = (pn - 18) >> 1, head = ((pn - 18) & 1) * 2 + (ct >> 7);
;                         dst = P + PL_QR + (size_t)qk * PL_QK_SZ + ((size_t)(bl * 4 + head) * 4096 + t) * 128 + (ct & 127); }
;                     else if (pn < 30) { const int vg = (pn - 22) >> 2, head = (pn - 22) & 3;
;                         dst = P + PL_VR + (size_t)vg * PL_VG_SZ + ((size_t)(bl * 4 + head) * 4096 + t) * 256 + ct; }
;                     else dst = G + (size_t)row * 2048 + (pn - 30) * 256 + ct;
;                     *(u32x4*)dst = w; } }
	v_pk_mul_f32 v[60:61], v[60:61], v[146:147] op_sel_hi:[1,0]
	v_cvt_pk_f16_f32 v62, v62, v63
	v_cvt_pk_f16_f32 v63, v64, v65
	v_cvt_pk_f16_f32 v64, v58, v59
	v_cvt_pk_f16_f32 v65, v60, v61
	v_add_u32_e32 v184, s55, v183
	global_store_dwordx4 v184, v[62:65], s[100:101]
	v_pk_mul_f32 v[46:47], v[46:47], v[146:147] op_sel:[0,1] op_sel_hi:[1,1]
	v_pk_mul_f32 v[48:49], v[48:49], v[146:147] op_sel:[0,1] op_sel_hi:[1,1]
	v_pk_mul_f32 v[42:43], v[42:43], v[146:147] op_sel:[0,1] op_sel_hi:[1,1]
	v_pk_mul_f32 v[44:45], v[44:45], v[146:147] op_sel:[0,1] op_sel_hi:[1,1]
	v_cvt_pk_f16_f32 v46, v46, v47
	v_cvt_pk_f16_f32 v47, v48, v49
	v_cvt_pk_f16_f32 v48, v42, v43
	v_cvt_pk_f16_f32 v49, v44, v45
	v_add_u32_e32 v185, s45, v184
	global_store_dwordx4 v185, v[46:49], s[100:101]
	v_pk_mul_f32 v[30:31], v[30:31], v[142:143] op_sel_hi:[1,0]
	v_pk_mul_f32 v[32:33], v[32:33], v[142:143] op_sel_hi:[1,0]
	v_pk_mul_f32 v[26:27], v[26:27], v[142:143] op_sel_hi:[1,0]
	v_pk_mul_f32 v[28:29], v[28:29], v[142:143] op_sel_hi:[1,0]
	v_cvt_pk_f16_f32 v30, v30, v31
	v_cvt_pk_f16_f32 v31, v32, v33
	v_cvt_pk_f16_f32 v32, v26, v27
	v_cvt_pk_f16_f32 v33, v28, v29
	v_add_u32_e32 v186, s45, v185
	global_store_dwordx4 v186, v[30:33], s[100:101]
	v_pk_mul_f32 v[14:15], v[14:15], v[142:143] op_sel:[0,1] op_sel_hi:[1,1]
	v_pk_mul_f32 v[16:17], v[16:17], v[142:143] op_sel:[0,1] op_sel_hi:[1,1]
	v_pk_mul_f32 v[10:11], v[10:11], v[142:143] op_sel:[0,1] op_sel_hi:[1,1]
	v_pk_mul_f32 v[12:13], v[12:13], v[142:143] op_sel:[0,1] op_sel_hi:[1,1]
	v_cvt_pk_f16_f32 v14, v14, v15
	v_cvt_pk_f16_f32 v15, v16, v17
	v_cvt_pk_f16_f32 v16, v10, v11
	v_cvt_pk_f16_f32 v17, v12, v13
	v_add_u32_e32 v187, s45, v186
	global_store_dwordx4 v187, v[14:17], s[100:101]
	v_pk_mul_f32 v[54:55], v[54:55], v[146:147] op_sel_hi:[1,0]
	v_pk_mul_f32 v[56:57], v[56:57], v[146:147] op_sel_hi:[1,0]
	v_pk_mul_f32 v[50:51], v[50:51], v[146:147] op_sel_hi:[1,0]
	v_pk_mul_f32 v[52:53], v[52:53], v[146:147] op_sel_hi:[1,0]
	v_cvt_pk_f16_f32 v54, v54, v55
	v_cvt_pk_f16_f32 v55, v56, v57
	v_cvt_pk_f16_f32 v56, v50, v51
	v_cvt_pk_f16_f32 v57, v52, v53
	v_add_u32_e32 v184, s27, v183
	global_store_dwordx4 v184, v[54:57], s[100:101]
	v_pk_mul_f32 v[38:39], v[38:39], v[146:147] op_sel:[0,1] op_sel_hi:[1,1]
	v_pk_mul_f32 v[40:41], v[40:41], v[146:147] op_sel:[0,1] op_sel_hi:[1,1]
	v_pk_mul_f32 v[34:35], v[34:35], v[146:147] op_sel:[0,1] op_sel_hi:[1,1]
	v_pk_mul_f32 v[36:37], v[36:37], v[146:147] op_sel:[0,1] op_sel_hi:[1,1]
	v_cvt_pk_f16_f32 v38, v38, v39
	v_cvt_pk_f16_f32 v39, v40, v41
	v_cvt_pk_f16_f32 v40, v34, v35
	v_cvt_pk_f16_f32 v41, v36, v37
	v_add_u32_e32 v185, s45, v184
	global_store_dwordx4 v185, v[38:41], s[100:101]
	v_pk_mul_f32 v[22:23], v[22:23], v[142:143] op_sel_hi:[1,0]
	v_pk_mul_f32 v[24:25], v[24:25], v[142:143] op_sel_hi:[1,0]
	v_pk_mul_f32 v[18:19], v[18:19], v[142:143] op_sel_hi:[1,0]
	v_pk_mul_f32 v[20:21], v[20:21], v[142:143] op_sel_hi:[1,0]
	v_cvt_pk_f16_f32 v22, v22, v23
	v_cvt_pk_f16_f32 v23, v24, v25
	v_cvt_pk_f16_f32 v24, v18, v19
	v_cvt_pk_f16_f32 v25, v20, v21
	v_add_u32_e32 v186, s45, v185
	global_store_dwordx4 v186, v[22:25], s[100:101]
	v_pk_mul_f32 v[6:7], v[6:7], v[142:143] op_sel:[0,1] op_sel_hi:[1,1]
	v_pk_mul_f32 v[8:9], v[8:9], v[142:143] op_sel:[0,1] op_sel_hi:[1,1]
	v_pk_mul_f32 v[2:3], v[2:3], v[142:143] op_sel:[0,1] op_sel_hi:[1,1]
	v_pk_mul_f32 v[4:5], v[4:5], v[142:143] op_sel:[0,1] op_sel_hi:[1,1]
	v_cvt_pk_f16_f32 v6, v6, v7
	v_cvt_pk_f16_f32 v7, v8, v9
	v_cvt_pk_f16_f32 v8, v2, v3
	v_cvt_pk_f16_f32 v9, v4, v5
	v_add_u32_e32 v187, s45, v186
	global_store_dwordx4 v187, v[6:9], s[100:101]
	s_mov_b32 s30, 0x8000
	s_mov_b32 s31, s65
	v_readlane_b32 s76, v253, 5
	v_readlane_b32 s77, v253, 6
	v_readlane_b32 s78, v253, 7
	v_readlane_b32 s79, v253, 8
	s_movk_i32 s80, 0x4000
	s_movk_i32 s81, 0x1000
	v_readlane_b32 s84, v255, 30
	s_mov_b32 s85, 0x11000
	s_mov_b32 s70, 1
	s_andn2_b64 vcc, exec, s[38:39]
	s_mov_b64 s[24:25], -1
	s_mov_b32 s56, 0x21000
	s_cbranch_vccnz .LBB0_149
	v_readlane_b32 s24, v255, 49
	v_readlane_b32 s25, v255, 50
	s_andn2_b64 vcc, exec, s[24:25]
	s_cbranch_vccnz .LBB0_148
	s_barrier
	s_branch .LBB0_148
